# weight-conversion queue: tickets fetched in batches of 2 (bounded by helper budget)
# baseline (speedup 1.0000x reference)
.LBB0_365:
	s_cmp_gt_u32 s26, 20
	s_cbranch_scc1 .LBB0_413
	s_cmp_eq_u32 s10, 2
	s_movk_i32 s0, 0x668
	s_movk_i32 s1, 0x12d0
	s_cselect_b32 s0, s0, 0x9ce
	s_cselect_b32 s1, 0x9ce, s1
	s_cmp_eq_u32 s10, 1
	s_cselect_b32 s8, 0, s0
	s_cselect_b32 s9, 0x668, s1
	s_lshl_b32 s0, s12, 5
	s_lshl_b32 s1, s10, 3
	s_or_b32 s30, s1, s0
	s_lshl_b64 s[0:1], s[30:31], 2
	s_add_u32 s0, s2, s0
	s_addc_u32 s1, s3, s1
	s_add_u32 s0, s0, 0x3c40
	s_addc_u32 s1, s1, 0
	s_sub_i32 s30, s9, s8
	s_mul_i32 s9, s12, 0x12d0
	s_add_i32 s80, s9, s8
	s_waitcnt lgkmcnt(0)
	v_ashrrev_i32_e32 v1, 4, v124
	s_movk_i32 s8, 0x104
	v_mul_lo_u32 v29, v1, s8
	v_and_b32_e32 v3, 3, v124
	v_and_b32_e32 v4, -4, v124
	s_movk_i32 s8, 0x1040
	v_mad_u32_u24 v31, v3, s8, v4
	s_movk_i32 s8, 0xc0
	s_addk_i32 s80, 0x12d0
	v_cmp_gt_i32_e64 s[38:39], s8, v124
	s_movk_i32 s8, 0x1800
	v_lshlrev_b32_e32 v30, 4, v3
	s_waitcnt vmcnt(0)
	v_lshlrev_b32_e32 v33, 11, v3
	v_lshlrev_b32_e32 v34, 6, v3
	v_cmp_eq_u32_e64 s[40:41], 0, v3
	v_mul_lo_u32 v3, v126, s8
	s_add_u32 s8, s2, 0x964e000
	s_addc_u32 s9, s3, 0
	s_add_u32 s10, s2, 0x804e000
	s_addc_u32 s11, s3, 0
	s_add_u32 s12, s2, 0x544e000
	s_addc_u32 s13, s3, 0
	s_add_u32 s14, s2, 0x4c4e000
	s_addc_u32 s15, s3, 0
	s_add_u32 s16, s2, 0x3c4e000
	s_addc_u32 s17, s3, 0
	s_add_u32 s18, s2, 0x4e000
	s_addc_u32 s19, s3, 0
	s_add_u32 s22, s2, 0x18dfe000
	s_addc_u32 s23, s3, 0
	s_cmp_lg_u64 s[2:3], 0
	v_ashrrev_i32_e32 v2, 2, v124
	s_cselect_b64 s[86:87], -1, 0
	v_lshlrev_b32_e32 v5, 2, v124
	v_cmp_gt_i32_e32 vcc, 32, v2
	s_and_b64 s[20:21], s[38:39], s[86:87]
	v_and_b32_e32 v0, 60, v5
	v_and_b32_e32 v6, 63, v124
	v_cndmask_b32_e64 v7, 32, 0, vcc
	s_add_u32 s26, s2, 0x4000
	s_mov_b32 s84, 0xd000
	s_movk_i32 s89, 0xfff
	s_mov_b32 s88, s82
	v_cmp_eq_u32_e64 s[36:37], 0, v124
	v_lshlrev_b32_e32 v28, 2, v0
	v_and_b32_e32 v4, 16, v30
	v_add_u32_e32 v32, v7, v2
	v_or_b32_e32 v35, v3, v6
	v_ashrrev_i32_e32 v3, 31, v2
	s_mov_b64 s[42:43], 0
	s_addc_u32 s27, s3, 0
	v_lshlrev_b32_e32 v6, 2, v6
	s_mov_b32 s90, 0
	s_branch .LBB0_371

.LBB0_371:
	s_cmp_eq_u32 s99, 0
	s_cbranch_scc1 .LBB0_412
	s_add_i32 s99, s99, -1
	s_cmp_eq_u32 s90, 0
	s_cbranch_scc1 .Ltb_fetch
	s_add_i32 s90, s90, -1
	s_add_i32 s91, s91, 1
	s_barrier
	v_mov_b32_e32 v7, s91
	s_branch .Ltb_have
.Ltb_fetch:
	s_min_u32 s92, s99, 1
	s_add_i32 s92, s92, 1
	s_barrier
	s_and_saveexec_b64 s[34:35], s[36:37]
	s_cbranch_execz .LBB0_375
	s_mov_b64 s[66:67], exec
	v_mbcnt_lo_u32_b32 v7, s66, 0
	v_mbcnt_hi_u32_b32 v7, s67, v7
	v_cmp_eq_u32_e32 vcc, 0, v7
	s_and_saveexec_b64 s[64:65], vcc
	s_cbranch_execz .LBB0_374
	s_bcnt1_i32_b64 s66, s[66:67]
	s_mul_i32 s66, s66, s92
	v_mov_b32_e32 v8, s66
	global_atomic_add v8, v117, v8, s[0:1] sc0

.LBB0_375:
	s_or_b64 exec, exec, s[34:35]
	s_mov_b64 s[34:35], src_shared_base
	v_mov_b32_e32 v121, s35
	s_waitcnt lgkmcnt(0)
	s_barrier
	flat_load_dword v7, v[120:121] sc0 sc1
	s_waitcnt vmcnt(0)
	v_readfirstlane_b32 s91, v7
	s_add_i32 s90, s92, -1
.Ltb_have:
	s_mov_b64 s[64:65], -1
	s_waitcnt lgkmcnt(0)
	v_cmp_gt_i32_e32 vcc, s30, v7
	s_and_saveexec_b64 s[34:35], vcc
	s_cbranch_execz .LBB0_370
	v_add_u32_e32 v7, s80, v7
	s_mov_b32 s64, 0x1b37484b
	v_mul_hi_i32 v8, v7, s64
	v_lshrrev_b32_e32 v9, 31, v8
	v_ashrrev_i32_e32 v8, 9, v8
	v_add_u32_e32 v8, v8, v9
	v_mul_i32_i24_e32 v9, 0x12d0, v8
	v_sub_u32_e32 v11, v7, v9
	s_movk_i32 s64, 0x77f
	v_cmp_lt_i32_e32 vcc, s64, v11
	s_and_saveexec_b64 s[64:65], vcc
	s_xor_b64 s[64:65], exec, s[64:65]
	s_cbranch_execz .LBB0_402
	s_movk_i32 s66, 0x97f
	v_cmp_lt_u32_e32 vcc, s66, v11
	s_and_saveexec_b64 s[66:67], vcc
	s_xor_b64 s[66:67], exec, s[66:67]
	s_cbranch_execz .LBB0_399
	s_movk_i32 s68, 0xa7f
	v_cmp_lt_u32_e32 vcc, s68, v11
	s_and_saveexec_b64 s[68:69], vcc
	s_xor_b64 s[68:69], exec, s[68:69]
	s_cbranch_execz .LBB0_396
	v_cmp_lt_u32_e32 vcc, s89, v11
	s_and_saveexec_b64 s[70:71], vcc
	s_xor_b64 s[70:71], exec, s[70:71]
	s_cbranch_execz .LBB0_385
	s_movk_i32 s72, 0x12bf
	v_cmp_lt_u32_e32 vcc, s72, v11
	s_and_saveexec_b64 s[72:73], vcc
	s_xor_b64 s[72:73], exec, s[72:73]
	s_cbranch_execz .LBB0_382
	v_add_u32_e32 v7, 0xffffed40, v11
	v_lshrrev_b32_e32 v116, 2, v7
	v_ashrrev_i32_e32 v9, 31, v8
	v_lshlrev_b64 v[12:13], 14, v[116:117]
	v_lshlrev_b64 v[8:9], 16, v[8:9]
	v_readlane_b32 s48, v255, 16
	v_lshlrev_b32_e32 v7, 6, v11
	v_lshlrev_b32_e32 v11, 5, v11
	v_lshl_add_u64 v[24:25], v[12:13], 0, v[8:9]
	v_readlane_b32 s54, v255, 22
	v_readlane_b32 s55, v255, 23
	v_and_b32_e32 v10, 64, v7
	v_and_b32_e32 v26, 64, v11
	v_lshl_add_u64 v[8:9], v[24:25], 2, s[54:55]
	v_add_u32_e32 v10, v10, v1
	v_lshlrev_b32_e32 v116, 2, v26
	v_lshl_add_u64 v[8:9], v[8:9], 0, v[116:117]
	v_lshlrev_b32_e32 v116, 2, v0
	v_ashrrev_i32_e32 v11, 31, v10
	v_lshl_add_u64 v[8:9], v[8:9], 0, v[116:117]
	v_lshlrev_b64 v[10:11], 9, v[10:11]
	v_lshl_add_u64 v[16:17], v[8:9], 0, v[10:11]
	s_movk_i32 s48, 0x2000
	v_add_co_u32_e32 v12, vcc, s48, v16
	s_movk_i32 s82, 0x4000
	s_nop 0
	v_addc_co_u32_e32 v13, vcc, 0, v17, vcc
	v_add_co_u32_e32 v18, vcc, s82, v16
	global_load_dwordx4 v[8:11], v[16:17], off nt
	s_nop 0
	global_load_dwordx4 v[12:15], v[12:13], off nt
	v_addc_co_u32_e32 v19, vcc, 0, v17, vcc
	v_add_co_u32_e32 v20, vcc, s33, v16
	v_readlane_b32 s49, v255, 17
	s_nop 0
	v_addc_co_u32_e32 v21, vcc, 0, v17, vcc
	global_load_dwordx4 v[16:19], v[18:19], off nt
	s_nop 0
	global_load_dwordx4 v[20:23], v[20:21], off nt
	v_readlane_b32 s50, v255, 18
	v_readlane_b32 s51, v255, 19
	v_readlane_b32 s52, v255, 20
	v_readlane_b32 s53, v255, 21
	v_readlane_b32 s56, v255, 24
	v_readlane_b32 s57, v255, 25
	v_readlane_b32 s58, v255, 26
	v_readlane_b32 s59, v255, 27
	v_readlane_b32 s60, v255, 28
	v_readlane_b32 s61, v255, 29
	v_readlane_b32 s62, v255, 30
	v_readlane_b32 s63, v255, 31
	v_lshl_add_u64 v[24:25], v[24:25], 1, s[8:9]
	v_add_u32_e32 v27, v28, v29
	s_waitcnt vmcnt(3)
	ds_write2_b32 v27, v8, v9 offset1:1
	ds_write2_b32 v27, v10, v11 offset0:2 offset1:3
	v_add_u32_e32 v8, 0x1040, v27
	s_waitcnt vmcnt(2)
	ds_write2_b32 v8, v12, v13 offset1:1
	v_add_u32_e32 v8, 0x1048, v27
	ds_write2_b32 v8, v14, v15 offset1:1
	v_add_u32_e32 v8, 0x2080, v27
	s_waitcnt vmcnt(1)
	ds_write2_b32 v8, v16, v17 offset1:1
	v_add_u32_e32 v8, 0x2088, v27
	ds_write2_b32 v8, v18, v19 offset1:1
	v_add_u32_e32 v8, 0x30c0, v27
	s_waitcnt vmcnt(0)
	ds_write2_b32 v8, v20, v21 offset1:1
	v_add_u32_e32 v8, 0x30c8, v27
	v_add_u32_e32 v14, 0x400, v31
	v_add_u32_e32 v18, 0x800, v31
	ds_write2_b32 v8, v22, v23 offset1:1
	s_waitcnt lgkmcnt(0)
	s_barrier
	ds_read2_b32 v[8:9], v31 offset1:65
	ds_read2_b32 v[10:11], v31 offset0:130 offset1:195
	ds_read2_b32 v[12:13], v14 offset0:4 offset1:69
	ds_read2_b32 v[14:15], v14 offset0:134 offset1:199
	ds_read2_b32 v[16:17], v18 offset0:8 offset1:73
	ds_read2_b32 v[18:19], v18 offset0:138 offset1:203
	v_add_u32_e32 v22, 0xc00, v31
	s_waitcnt lgkmcnt(5)
	v_cvt_pk_bf16_f32 v8, v8, v9
	s_waitcnt lgkmcnt(4)
	v_cvt_pk_bf16_f32 v9, v10, v11
	s_waitcnt lgkmcnt(3)
	v_cvt_pk_bf16_f32 v10, v12, v13
	s_waitcnt lgkmcnt(0)
	v_cvt_pk_bf16_f32 v13, v18, v19
	v_add_u32_e32 v18, v26, v2
	v_cvt_pk_bf16_f32 v12, v16, v17
	v_ashrrev_i32_e32 v16, 7, v18
	v_or_b32_e32 v7, v7, v30
	v_ashrrev_i32_e32 v17, 31, v16
	ds_read2_b32 v[20:21], v22 offset0:12 offset1:77
	ds_read2_b32 v[22:23], v22 offset0:142 offset1:207
	v_lshlrev_b64 v[16:17], 15, v[16:17]
	v_lshlrev_b32_e32 v7, 8, v7
	v_and_b32_e32 v116, 0x6000, v7
	v_lshl_add_u64 v[16:17], v[24:25], 0, v[16:17]
	v_lshlrev_b32_e32 v7, 6, v18
	v_lshl_add_u64 v[16:17], v[16:17], 0, v[116:117]
	v_and_b32_e32 v116, 0x1fc0, v7
	v_lshl_add_u64 v[16:17], v[16:17], 0, v[116:117]
	v_lshlrev_b32_e32 v116, 1, v4
	v_cvt_pk_bf16_f32 v11, v14, v15
	v_lshl_add_u64 v[16:17], v[16:17], 0, v[116:117]
	s_waitcnt lgkmcnt(1)
	v_cvt_pk_bf16_f32 v14, v20, v21
	s_waitcnt lgkmcnt(0)
	v_cvt_pk_bf16_f32 v15, v22, v23
	global_store_dwordx4 v[16:17], v[8:11], off
	global_store_dwordx4 v[16:17], v[12:15], off offset:16
	s_barrier
